# attention: waves 4-7 start each tile pair 128 cycles after their SIMD partners (s_sleep 2 after the pair barrier) so the two identical instruction streams do not collide
# speedup vs baseline: 1.0202x; 1.0093x over previous
.Latt_even_entry:
	s_waitcnt vmcnt(0) lgkmcnt(0)
	s_barrier
	s_bitcmp1_b32 s97, 8
	s_cbranch_scc0 .Latt_no_skew
	s_sleep 2
.Latt_no_skew:
	s_cmp_lg_u32 s26, 0
	s_cbranch_scc1 .Latt_q_resident
	ds_read_b128 v[230:233], v209
	ds_read_b128 v[234:237], v209 offset:32
	ds_read_b128 v[242:245], v209 offset:64
	ds_read_b128 v[246:249], v209 offset:96
	v_mov_b32_e32 v238, s18
	ds_read_b32 v238, v238
